# attention loop: s_setprio 2 over the QK and PV MFMA segments
# baseline (speedup 1.0000x reference)
; #define MFMA(a, b, c) __builtin_amdgcn_mfma_f32_32x32x16_bf16((a), (b), (c), 0, 0, 0)
; DI f32x16 zero16() { f32x16 z; _Pragma("unroll") for (int i = 0; i < 16; ++i) z[i] = 0.f; return z; }
; DI void attn_item(const Params& p, const bf16_t* Qbase  , int bh, int q0, int nkeys, int out_row0, unsigned char* smem) {
;     ...
;     for (int kt = 0; kt < nkt; ++kt) {
;         const int buf = kt & 1;
;         if (kt + 1 < nkt) gload(kt + 1);
;         __builtin_amdgcn_sched_barrier(0);
;         f32x16 s0 = zero16(), s1 = zero16();
;         const bf16_t* kb = Ks + (buf * 64 + li) * KS + 8 * lh;
; #pragma unroll
;         for (int ks = 0; ks < 6; ++ks) { s0 = MFMA(ld8(kb + 16 * ks), qf[ks], s0); s1 = MFMA(ld8(kb + 32 * KS + 16 * ks), qf[ks], s1); }
;         float mx = fmaxf(s0[0], s1[0]);
; #pragma unroll
;         for (int r = 1; r < 16; ++r) mx = fmaxf(fmaxf(mx, s0[r]), s1[r]);
;         mx = fmaxf(mx, __shfl_xor(mx, 32));
;         const float mn = fmaxf(m, mx);
;         if (__any(mn > m)) {
;             const float corr = __builtin_amdgcn_exp2f((m - mn) * scl);
;             l *= corr;
; #pragma unroll
;             for (int r = 0; r < 16; ++r) { o0[r] *= corr; o1[r] *= corr; }
;             m = mn;
;         }
.LBB0_414:
	global_load_dwordx4 v[108:111], v122, s[26:27]
	global_load_dwordx4 v[104:107], v124, s[26:27]
	global_load_dwordx4 v[100:103], v126, s[26:27]
	global_load_dwordx4 v[96:99], v118, s[26:27]
	global_load_dwordx4 v[92:95], v120, s[26:27]
	s_and_b32 s9, s8, 64
	s_mul_i32 s12, s9, 0xd0
	v_add_u32_e32 v137, s12, v154
	ds_read_b128 v[202:205], v137
	ds_read_b128 v[206:209], v137 offset:6656
	ds_read_b128 v[210:213], v137 offset:32
	ds_read_b128 v[214:217], v137 offset:6688
	ds_read_b128 v[218:221], v137 offset:64
	s_setprio 2
	s_waitcnt lgkmcnt(4)
	v_mfma_f32_32x32x16_bf16 v[36:51], v[202:205], v[88:91], 0
	ds_read_b128 v[202:205], v137 offset:6720
	s_waitcnt lgkmcnt(4)
	v_mfma_f32_32x32x16_bf16 v[52:67], v[206:209], v[88:91], 0
	ds_read_b128 v[206:209], v137 offset:96
	s_waitcnt lgkmcnt(4)
	v_mfma_f32_32x32x16_bf16 v[36:51], v[210:213], v[84:87], v[36:51]
	ds_read_b128 v[210:213], v137 offset:6752
	s_waitcnt lgkmcnt(4)
	v_mfma_f32_32x32x16_bf16 v[52:67], v[214:217], v[84:87], v[52:67]
	ds_read_b128 v[214:217], v137 offset:128
	s_waitcnt lgkmcnt(4)
	v_mfma_f32_32x32x16_bf16 v[36:51], v[218:221], v[80:83], v[36:51]
	ds_read_b128 v[218:221], v137 offset:6784
	s_waitcnt lgkmcnt(4)
	v_mfma_f32_32x32x16_bf16 v[52:67], v[202:205], v[80:83], v[52:67]
	ds_read_b128 v[202:205], v137 offset:160
	s_waitcnt lgkmcnt(4)
	v_mfma_f32_32x32x16_bf16 v[36:51], v[206:209], v[76:79], v[36:51]
	ds_read_b128 v[206:209], v137 offset:6816
	s_waitcnt lgkmcnt(4)
	v_mfma_f32_32x32x16_bf16 v[52:67], v[210:213], v[76:79], v[52:67]
	s_waitcnt lgkmcnt(3)
	v_mfma_f32_32x32x16_bf16 v[36:51], v[214:217], v[72:75], v[36:51]
	s_waitcnt lgkmcnt(2)
	v_mfma_f32_32x32x16_bf16 v[52:67], v[218:221], v[72:75], v[52:67]
	s_waitcnt lgkmcnt(1)
	v_mfma_f32_32x32x16_bf16 v[36:51], v[202:205], v[68:71], v[36:51]
	s_waitcnt lgkmcnt(0)
	v_mfma_f32_32x32x16_bf16 v[52:67], v[206:209], v[68:71], v[52:67]
	s_setprio 0
	s_mul_i32 s13, s9, 0x88
	v_add_u32_e32 v148, s13, v155
	v_add_u32_e32 v151, s13, v156
	s_nop 9
	v_max3_f32 v137, v36, v37, v38
	v_max3_f32 v139, v52, v53, v54
	v_max3_f32 v137, v137, v39, v40
	v_max3_f32 v139, v139, v55, v56
	v_max3_f32 v137, v137, v41, v42
	v_max3_f32 v139, v139, v57, v58
	v_max3_f32 v137, v137, v43, v44
	v_max3_f32 v139, v139, v59, v60
	v_max3_f32 v137, v137, v45, v46
	v_max3_f32 v139, v139, v61, v62
	v_max3_f32 v137, v137, v47, v48
	v_max3_f32 v139, v139, v63, v64
	v_max3_f32 v137, v137, v49, v50
	v_max3_f32 v139, v139, v65, v66
	v_max3_f32 v137, v137, v51, v139
	v_max_f32_e32 v137, v137, v67
	v_mov_b32_e32 v140, v137
	v_mov_b32_e32 v141, v137
	s_nop 1
	v_permlane32_swap_b32_e32 v140, v141
	v_max3_f32 v139, v137, v140, v141
	v_max_f32_e32 v137, v136, v139
	v_cmp_gt_f32_e32 vcc, v137, v136
	s_cbranch_vccz .Lattn_keep
	v_sub_f32_e32 v136, v136, v137
	v_mul_f32_e32 v136, 0x3e16c740, v136
	v_exp_f32_e32 v136, v136
	s_nop 0
	v_pk_mul_f32 v[4:5], v[4:5], v[136:137] op_sel_hi:[1,0]
	v_pk_mul_f32 v[6:7], v[6:7], v[136:137] op_sel_hi:[1,0]
	v_pk_mul_f32 v[8:9], v[8:9], v[136:137] op_sel_hi:[1,0]
	v_pk_mul_f32 v[10:11], v[10:11], v[136:137] op_sel_hi:[1,0]
	v_pk_mul_f32 v[12:13], v[12:13], v[136:137] op_sel_hi:[1,0]
	v_pk_mul_f32 v[14:15], v[14:15], v[136:137] op_sel_hi:[1,0]
	v_pk_mul_f32 v[16:17], v[16:17], v[136:137] op_sel_hi:[1,0]
	v_pk_mul_f32 v[18:19], v[18:19], v[136:137] op_sel_hi:[1,0]
	v_pk_mul_f32 v[20:21], v[20:21], v[136:137] op_sel_hi:[1,0]
	v_pk_mul_f32 v[22:23], v[22:23], v[136:137] op_sel_hi:[1,0]
	v_pk_mul_f32 v[24:25], v[24:25], v[136:137] op_sel_hi:[1,0]
	v_pk_mul_f32 v[26:27], v[26:27], v[136:137] op_sel_hi:[1,0]
	v_pk_mul_f32 v[28:29], v[28:29], v[136:137] op_sel_hi:[1,0]
	v_pk_mul_f32 v[30:31], v[30:31], v[136:137] op_sel_hi:[1,0]
	v_pk_mul_f32 v[32:33], v[32:33], v[136:137] op_sel_hi:[1,0]
	v_pk_mul_f32 v[34:35], v[34:35], v[136:137] op_sel_hi:[1,0]
	v_mul_f32_e32 v0, v0, v136
; #define MFMA(a, b, c) __builtin_amdgcn_mfma_f32_32x32x16_bf16((a), (b), (c), 0, 0, 0)
; DI void attn_item(const Params& p, const bf16_t* Qbase  , int bh, int q0, int nkeys, int out_row0, unsigned char* smem) {
;     ...
;         const float nb = -m * scl;
;         float sum0 = 0.f, sum1 = 0.f;
; #pragma unroll
;         for (int r = 0; r < 16; ++r) { s0[r] = __builtin_amdgcn_exp2f(fmaf(s0[r], scl, nb)); s1[r] = __builtin_amdgcn_exp2f(fmaf(s1[r], scl, nb)); sum0 += s0[r]; sum1 += s1[r]; }
;         float sum = sum0 + sum1;
;         sum += __shfl_xor(sum, 32);
;         l += sum;
;         bf16x8 pf[2][2];
;         pf[0][0] = pack8(s0[0], s0[1], s0[2], s0[3], s0[4], s0[5], s0[6], s0[7]); pf[0][1] = pack8(s0[8], s0[9], s0[10], s0[11], s0[12], s0[13], s0[14], s0[15]);
;         pf[1][0] = pack8(s1[0], s1[1], s1[2], s1[3], s1[4], s1[5], s1[6], s1[7]); pf[1][1] = pack8(s1[8], s1[9], s1[10], s1[11], s1[12], s1[13], s1[14], s1[15]);
;         const bf16_t* vb = Vs + (buf * 64 + li) * VS + 4 * lh;
; #pragma unroll
;         for (int j = 0; j < 2; ++j)
; #pragma unroll
;             for (int s = 0; s < 2; ++s) {
;                 const int ko = 32 * j + 16 * s;
;                 o0 = MFMA(ld4x2(vb + ko, vb + ko + 8), pf[j][s], o0);
;                 o1 = MFMA(ld4x2(vb + 32 * VS + ko, vb + 32 * VS + ko + 8), pf[j][s], o1);
;             }
;         __builtin_amdgcn_sched_barrier(0);
;         if (kt + 1 < nkt) sstore(buf ^ 1);
;         __syncthreads();
;     }
.Lattn_keep:
	v_mul_f32_e32 v136, 0xbe16c740, v137
	v_fmamk_f32 v36, v36, 0x3e16c740, v136
	v_fmamk_f32 v37, v37, 0x3e16c740, v136
	v_exp_f32_e32 v36, v36
	v_fmamk_f32 v38, v38, 0x3e16c740, v136
	v_exp_f32_e32 v37, v37
	v_fmamk_f32 v39, v39, 0x3e16c740, v136
	v_exp_f32_e32 v38, v38
	v_fmamk_f32 v40, v40, 0x3e16c740, v136
	v_exp_f32_e32 v39, v39
	v_fmamk_f32 v41, v41, 0x3e16c740, v136
	v_exp_f32_e32 v40, v40
	v_fmamk_f32 v42, v42, 0x3e16c740, v136
	v_exp_f32_e32 v41, v41
	v_fmamk_f32 v43, v43, 0x3e16c740, v136
	v_exp_f32_e32 v42, v42
	v_fmamk_f32 v44, v44, 0x3e16c740, v136
	v_exp_f32_e32 v43, v43
	v_fmamk_f32 v45, v45, 0x3e16c740, v136
	v_exp_f32_e32 v44, v44
	v_fmamk_f32 v46, v46, 0x3e16c740, v136
	v_exp_f32_e32 v45, v45
	v_fmamk_f32 v47, v47, 0x3e16c740, v136
	v_exp_f32_e32 v46, v46
	v_fmamk_f32 v48, v48, 0x3e16c740, v136
	v_exp_f32_e32 v47, v47
	v_fmamk_f32 v49, v49, 0x3e16c740, v136
	v_exp_f32_e32 v48, v48
	v_fmamk_f32 v50, v50, 0x3e16c740, v136
	v_exp_f32_e32 v49, v49
	v_fmamk_f32 v51, v51, 0x3e16c740, v136
	v_exp_f32_e32 v50, v50
	v_fmamk_f32 v52, v52, 0x3e16c740, v136
	v_exp_f32_e32 v51, v51
	v_fmamk_f32 v53, v53, 0x3e16c740, v136
	v_exp_f32_e32 v52, v52
	v_fmamk_f32 v54, v54, 0x3e16c740, v136
	v_exp_f32_e32 v53, v53
	v_fmamk_f32 v55, v55, 0x3e16c740, v136
	v_exp_f32_e32 v54, v54
	v_fmamk_f32 v56, v56, 0x3e16c740, v136
	v_exp_f32_e32 v55, v55
	v_fmamk_f32 v57, v57, 0x3e16c740, v136
	v_exp_f32_e32 v56, v56
	v_fmamk_f32 v58, v58, 0x3e16c740, v136
	v_exp_f32_e32 v57, v57
	v_fmamk_f32 v59, v59, 0x3e16c740, v136
	v_exp_f32_e32 v58, v58
	v_fmamk_f32 v60, v60, 0x3e16c740, v136
	v_exp_f32_e32 v59, v59
	v_fmamk_f32 v61, v61, 0x3e16c740, v136
	v_exp_f32_e32 v60, v60
	v_fmamk_f32 v62, v62, 0x3e16c740, v136
	v_exp_f32_e32 v61, v61
	v_fmamk_f32 v63, v63, 0x3e16c740, v136
	v_exp_f32_e32 v62, v62
	v_fmamk_f32 v64, v64, 0x3e16c740, v136
	v_exp_f32_e32 v63, v63
	v_fmamk_f32 v65, v65, 0x3e16c740, v136
	v_exp_f32_e32 v64, v64
	v_fmamk_f32 v66, v66, 0x3e16c740, v136
	v_exp_f32_e32 v65, v65
	v_fmamk_f32 v67, v67, 0x3e16c740, v136
	v_exp_f32_e32 v66, v66
	v_exp_f32_e32 v67, v67
	v_add_f32_e32 v138, v36, v37
	v_add_f32_e32 v139, v44, v45
	v_add_f32_e32 v152, v52, v53
	v_add_f32_e32 v153, v60, v61
	v_add_f32_e32 v138, v138, v38
	v_add_f32_e32 v139, v139, v46
	v_add_f32_e32 v152, v152, v54
	v_add_f32_e32 v153, v153, v62
	v_add_f32_e32 v138, v138, v39
	v_add_f32_e32 v139, v139, v47
	v_add_f32_e32 v152, v152, v55
	v_add_f32_e32 v153, v153, v63
	v_add_f32_e32 v138, v138, v40
	v_add_f32_e32 v139, v139, v48
	v_add_f32_e32 v152, v152, v56
	v_add_f32_e32 v153, v153, v64
	v_add_f32_e32 v138, v138, v41
	v_add_f32_e32 v139, v139, v49
	v_add_f32_e32 v152, v152, v57
	v_add_f32_e32 v153, v153, v65
	v_add_f32_e32 v138, v138, v42
	v_add_f32_e32 v139, v139, v50
	v_add_f32_e32 v152, v152, v58
	v_add_f32_e32 v153, v153, v66
	v_add_f32_e32 v138, v138, v43
	v_add_f32_e32 v139, v139, v51
	v_add_f32_e32 v152, v152, v59
	v_add_f32_e32 v153, v153, v67
	v_cvt_pk_bf16_f32 v140, v52, v53
	v_cvt_pk_bf16_f32 v141, v54, v55
	v_cvt_pk_bf16_f32 v142, v56, v57
	v_cvt_pk_bf16_f32 v143, v58, v59
	v_cvt_pk_bf16_f32 v144, v60, v61
	v_cvt_pk_bf16_f32 v145, v62, v63
	v_cvt_pk_bf16_f32 v146, v64, v65
	v_cvt_pk_bf16_f32 v147, v66, v67
	ds_read2_b64 v[52:55], v148 offset1:2
	ds_read2_b64 v[56:59], v151 offset0:32 offset1:34
	ds_read2_b64 v[60:63], v148 offset0:4 offset1:6
	ds_read2_b64 v[64:67], v151 offset0:36 offset1:38
	v_cvt_pk_bf16_f32 v36, v36, v37
	v_cvt_pk_bf16_f32 v37, v38, v39
	v_cvt_pk_bf16_f32 v38, v40, v41
	v_cvt_pk_bf16_f32 v39, v42, v43
	v_cvt_pk_bf16_f32 v40, v44, v45
	v_cvt_pk_bf16_f32 v41, v46, v47
	v_cvt_pk_bf16_f32 v42, v48, v49
	v_cvt_pk_bf16_f32 v43, v50, v51
	v_add_f32_e32 v138, v138, v139
	v_add_f32_e32 v152, v152, v153
	v_add_f32_e32 v138, v138, v152
	v_add_f32_e32 v0, v0, v138
	s_setprio 2
	s_waitcnt lgkmcnt(3)
	v_mfma_f32_32x32x16_bf16 v[4:19], v[52:55], v[36:39], v[4:19]
	ds_read2_b64 v[52:55], v148 offset0:8 offset1:10
	s_waitcnt lgkmcnt(3)
	v_mfma_f32_32x32x16_bf16 v[20:35], v[56:59], v[36:39], v[20:35]
	ds_read2_b64 v[56:59], v151 offset0:40 offset1:42
	s_waitcnt lgkmcnt(3)
	v_mfma_f32_32x32x16_bf16 v[4:19], v[60:63], v[40:43], v[4:19]
	ds_read2_b64 v[60:63], v148 offset0:12 offset1:14
	s_waitcnt lgkmcnt(3)
	v_mfma_f32_32x32x16_bf16 v[20:35], v[64:67], v[40:43], v[20:35]
	ds_read2_b64 v[64:67], v151 offset0:44 offset1:46
	s_waitcnt lgkmcnt(3)
	v_mfma_f32_32x32x16_bf16 v[4:19], v[52:55], v[140:143], v[4:19]
	s_waitcnt lgkmcnt(2)
	v_mfma_f32_32x32x16_bf16 v[20:35], v[56:59], v[140:143], v[20:35]
	s_waitcnt lgkmcnt(1)
	v_mfma_f32_32x32x16_bf16 v[4:19], v[60:63], v[144:147], v[4:19]
	s_waitcnt lgkmcnt(0)
	v_mfma_f32_32x32x16_bf16 v[20:35], v[64:67], v[144:147], v[20:35]
	s_setprio 0
	s_xor_b32 s9, s9, 64
	s_mul_i32 s12, s9, 0xd0
	s_mul_i32 s13, s9, 0x88
	v_add_u32_e32 v36, s12, v157
	s_waitcnt vmcnt(4)
	ds_write_b128 v36, v[108:111]
	v_add_u32_e32 v36, s12, v158
	s_waitcnt vmcnt(3)
	ds_write_b128 v36, v[104:107]
	v_add_u32_e32 v36, s12, v159
	s_waitcnt vmcnt(2)
	ds_write_b128 v36, v[100:103]
	v_add_u32_e32 v36, s13, v160
	s_waitcnt vmcnt(1)
	ds_write2_b64 v36, v[96:97], v[98:99] offset1:1
	v_add_u32_e32 v36, s13, v161
	s_add_i32 s8, s8, 64
	v_add_u32_e32 v122, 0x3000, v122
	v_add_u32_e32 v124, 0x3000, v124
	v_add_u32_e32 v126, 0x3000, v126
	v_add_u32_e32 v118, 0x80, v118
	v_add_u32_e32 v120, 0x80, v120
	s_mov_b64 s[10:11], 0x3000
	s_movk_i32 s12, 0x88
	s_movk_i32 s13, 0xd0
	s_movk_i32 s37, 0xd0
	s_movk_i32 s71, 0x88
	s_mov_b64 s[68:69], 0x3000
	s_waitcnt vmcnt(0)
	ds_write2_b64 v36, v[92:93], v[94:95] offset1:1
	s_waitcnt lgkmcnt(0)
	s_barrier
	s_cmpk_eq_i32 s8, 0x10c0
	s_cbranch_scc1 .Lattn_exit
	v_mov_b32_e32 v136, v137
	s_branch .LBB0_414
